# prologue weight-transpose items: wait only for the LDS scratch reads after an item's stores
# speedup vs baseline: 1.0066x; 1.0015x over previous
; __device__ __forceinline__ unsigned pk2(float lo, float hi) { unsigned r; asm("v_cvt_pk_bf16_f32 %0, %1, %2" : "=v"(r) : "v"(lo), "v"(hi)); return r; }
; __device__ __forceinline__ void transpose_item(const float* W, int ldw, int src0, int nvalid, int k0, int K, bf16_t* WT, int drow0, float* scr, int lane) {
;     ...
;     for (int i = 0; i < 32; ++i) { const int kk = 2 * i + (lane >> 5); tv[i] = (n_ < nvalid) ? W[(size_t)(k0 + kk) * ldw + src0 + n_] : 0.f; }
; #pragma unroll
;     for (int i = 0; i < 32; ++i) { const int kk = 2 * i + (lane >> 5); scr[kk * 33 + n_] = tv[i]; }
;     __builtin_amdgcn_s_waitcnt(0); asm volatile("" ::: "memory");
;     const int c = lane & 7;
; #pragma unroll
;     for (int j = 0; j < 4; ++j) { const int n = (lane >> 3) + 8 * j; const float* s = scr + (8 * c) * 33 + n;
;         u32x4 o; o.x = pk2(s[0 * 33], s[1 * 33]); o.y = pk2(s[2 * 33], s[3 * 33]); o.z = pk2(s[4 * 33], s[5 * 33]); o.w = pk2(s[6 * 33], s[7 * 33]);
;         *(u32x4*)(WT + (size_t)(drow0 + n) * K + k0 + 8 * c) = o; }
;     __builtin_amdgcn_s_waitcnt(0); asm volatile("" ::: "memory");
.LBB0_8:
	s_or_b64 exec, exec, s[0:1]
	s_waitcnt vmcnt(0)
	ds_write2_b32 v33, v49, v50 offset1:66
	ds_write2_b32 v33, v52, v51 offset0:132 offset1:198
	ds_write2_b32 v40, v54, v53 offset0:8 offset1:74
	ds_write2_b32 v40, v56, v55 offset0:140 offset1:206
	ds_write2_b32 v41, v58, v57 offset0:16 offset1:82
	ds_write2_b32 v41, v60, v59 offset0:148 offset1:214
	ds_write2_b32 v42, v62, v61 offset0:24 offset1:90
	ds_write2_b32 v42, v64, v63 offset0:156 offset1:222
	ds_write2_b32 v43, v66, v65 offset0:32 offset1:98
	ds_write2_b32 v43, v68, v67 offset0:164 offset1:230
	ds_write2_b32 v44, v70, v69 offset0:40 offset1:106
	ds_write2_b32 v44, v72, v71 offset0:172 offset1:238
	ds_write2_b32 v45, v74, v73 offset0:48 offset1:114
	ds_write2_b32 v45, v76, v75 offset0:180 offset1:246
	ds_write2_b32 v46, v78, v77 offset0:56 offset1:122
	ds_write2_b32 v46, v80, v79 offset0:188 offset1:254
	s_waitcnt vmcnt(0) expcnt(0) lgkmcnt(0)
	v_sub_u32_e32 v2, 0, v2
	ds_read2_b32 v[50:51], v35 offset0:33 offset1:41
	ds_read2_b32 v[52:53], v35 offset1:8
	ds_read2_b32 v[54:55], v35 offset0:66 offset1:74
	ds_read2_b32 v[56:57], v35 offset0:99 offset1:107
	ds_read2_b32 v[58:59], v35 offset0:132 offset1:140
	ds_read2_b32 v[60:61], v35 offset0:165 offset1:173
	ds_read2_b32 v[62:63], v35 offset0:198 offset1:206
	ds_read2_b32 v[64:65], v35 offset0:231 offset1:239
	v_add3_u32 v68, v34, v39, v2
	v_ashrrev_i32_e32 v29, 31, v28
	v_ashrrev_i32_e32 v69, 31, v68
	v_lshl_add_u64 v[66:67], v[28:29], 1, v[14:15]
	v_lshlrev_b64 v[70:71], 12, v[68:69]
	s_waitcnt lgkmcnt(6)
	v_cvt_pk_bf16_f32 v28, v52, v50
	v_lshl_add_u64 v[70:71], v[66:67], 0, v[70:71]
	v_add_u32_e32 v50, 8, v68
	s_waitcnt lgkmcnt(4)
	v_cvt_pk_bf16_f32 v29, v54, v56
	s_waitcnt lgkmcnt(2)
	v_cvt_pk_bf16_f32 v30, v58, v60
	s_waitcnt lgkmcnt(0)
	v_cvt_pk_bf16_f32 v31, v62, v64
	global_store_dwordx4 v[70:71], v[28:31], off
	s_nop 1
	v_cvt_pk_bf16_f32 v28, v53, v51
	v_ashrrev_i32_e32 v51, 31, v50
	v_lshlrev_b64 v[50:51], 12, v[50:51]
	v_cvt_pk_bf16_f32 v29, v55, v57
	v_cvt_pk_bf16_f32 v30, v59, v61
	v_cvt_pk_bf16_f32 v31, v63, v65
	v_lshl_add_u64 v[50:51], v[66:67], 0, v[50:51]
	ds_read2_b32 v[52:53], v35 offset0:16 offset1:24
	ds_read2_b32 v[54:55], v35 offset0:49 offset1:57
	ds_read2_b32 v[56:57], v35 offset0:82 offset1:90
	ds_read2_b32 v[58:59], v35 offset0:115 offset1:123
	ds_read2_b32 v[60:61], v35 offset0:148 offset1:156
	ds_read2_b32 v[62:63], v35 offset0:181 offset1:189
	ds_read2_b32 v[64:65], v35 offset0:214 offset1:222
	ds_read2_b32 v[70:71], v35 offset0:247 offset1:255
	global_store_dwordx4 v[50:51], v[28:31], off
	v_add_u32_e32 v50, 16, v68
	v_ashrrev_i32_e32 v51, 31, v50
	v_lshlrev_b64 v[50:51], 12, v[50:51]
	v_lshl_add_u64 v[50:51], v[66:67], 0, v[50:51]
	s_waitcnt lgkmcnt(6)
	v_cvt_pk_bf16_f32 v28, v52, v54
	s_waitcnt lgkmcnt(4)
	v_cvt_pk_bf16_f32 v29, v56, v58
	s_waitcnt lgkmcnt(2)
	v_cvt_pk_bf16_f32 v30, v60, v62
	s_waitcnt lgkmcnt(0)
	v_cvt_pk_bf16_f32 v31, v64, v70
	global_store_dwordx4 v[50:51], v[28:31], off
	v_add_u32_e32 v50, 24, v68
	v_ashrrev_i32_e32 v51, 31, v50
	v_lshlrev_b64 v[50:51], 12, v[50:51]
	v_lshl_add_u64 v[50:51], v[66:67], 0, v[50:51]
	v_cvt_pk_bf16_f32 v28, v53, v55
	v_cvt_pk_bf16_f32 v29, v57, v59
	v_cvt_pk_bf16_f32 v30, v61, v63
	v_cvt_pk_bf16_f32 v31, v65, v71
	global_store_dwordx4 v[50:51], v[28:31], off
	s_waitcnt lgkmcnt(0)

; __device__ __forceinline__ void transpose_item(const float* W, int ldw, int src0, int nvalid, int k0, int K, bf16_t* WT, int drow0, float* scr, int lane) {
;     ...
;     for (int i = 0; i < 32; ++i) { const int kk = 2 * i + (lane >> 5); tv[i] = (n_ < nvalid) ? W[(size_t)(k0 + kk) * ldw + src0 + n_] : 0.f; }
; __device__ __forceinline__ void phase_prologue(const Params& p, unsigned char* lds) {
;     ...
;         if (r < I_IN) { const int kb = r / 360, nb = r % 360, n0 = nb * 32; int src0, nv;
;             if (n0 < 7168) { src0 = n0; nv = 32; } else if (n0 < 11264) { src0 = n0 + 16; nv = 32; } else if (n0 == 11264) { src0 = 7168; nv = 16; } else { src0 = 0; nv = 0; }
;             transpose_item(p.in[1], 11280, src0, nv, kb * 64, 2048, (bf16_t*)(ws + WS_WIN), n0, scr, lane); continue; }
;         r -= I_IN;
;         if (r < I_BN) { const int kb = r / 64, nb = r % 64; transpose_item(p.in[8], 2048, nb * 32, 32, kb * 64, 1024, (bf16_t*)(ws + WS_WBNA), nb * 32, scr, lane); continue; }
;         r -= I_BN;
;         if (r < I_BN) { const int kb = r / 64, nb = r % 64; transpose_item(p.in[9], 2048, nb * 32, 32, kb * 64, 1024, (bf16_t*)(ws + WS_WBML), nb * 32, scr, lane); continue; }
;         r -= I_BN;
;         if (r < I_OUT) { const int kb = r / 64, nb = r % 64; transpose_item(p.in[10], 2048, nb * 32, 32, kb * 64, 2048, (bf16_t*)(ws + WS_WOUT), nb * 32, scr, lane); continue; }
;         r -= I_OUT;
;         if (r < I_UP) { const int kb = r / 344, nb = r % 344, n0 = nb * 32, pt = n0 >> 8, l0 = n0 & 255;
;             const int src0 = (l0 < 128) ? pt * 128 + l0 : DFF + pt * 128 + (l0 - 128);
;             transpose_item(p.in[13], NUP, src0, 32, kb * 64, 2048, (bf16_t*)(ws + WS_WUP), n0, scr, lane); continue; }
;         r -= I_UP;
;         { const int kb = r / 64, nb = r % 64; transpose_item(p.in[16], 2048, nb * 32, 32, kb * 64, DFF, (bf16_t*)(ws + WS_WDN), nb * 32, scr, lane); }
.LBB0_10:
	s_movk_i32 s0, 0x2cff
	v_cmp_lt_i32_e64 s[0:1], s0, v1
	s_and_saveexec_b64 s[8:9], s[0:1]
	s_xor_b64 s[8:9], exec, s[8:9]
	s_cbranch_execz .LBB0_28
	s_movk_i32 s0, 0x30ff
	v_cmp_lt_u32_e64 s[0:1], s0, v1
	s_and_saveexec_b64 s[10:11], s[0:1]
	s_xor_b64 s[10:11], exec, s[10:11]
	s_cbranch_execz .LBB0_25
	s_movk_i32 s0, 0x34ff
	v_cmp_lt_u32_e64 s[0:1], s0, v1
	s_and_saveexec_b64 s[12:13], s[0:1]
	s_xor_b64 s[12:13], exec, s[12:13]
	s_cbranch_execz .LBB0_22
	s_movk_i32 s0, 0x3cff
	v_cmp_lt_u32_e64 s[0:1], s0, v1
	s_and_saveexec_b64 s[14:15], s[0:1]
	s_xor_b64 s[14:15], exec, s[14:15]
	s_cbranch_execz .LBB0_19
	s_movk_i32 s0, 0x67ff
	v_cmp_lt_u32_e64 s[0:1], s0, v1
	s_and_saveexec_b64 s[18:19], s[0:1]
	s_xor_b64 s[0:1], exec, s[18:19]
	s_cbranch_execz .LBB0_16
	v_and_b32_e32 v2, 0x7fffffc0, v1
	v_add_u32_e32 v28, 0xffff9800, v2
	v_and_b32_e32 v49, 0x7e0, v39
	v_or_b32_e32 v30, v28, v32
	v_lshlrev_b32_e32 v2, 2, v49
	v_lshl_add_u64 v[50:51], v[16:17], 0, v[2:3]
	v_or_b32_e32 v2, 2, v30
	v_lshlrev_b64 v[54:55], 13, v[2:3]
	v_or_b32_e32 v2, 4, v30
	v_lshlrev_b64 v[56:57], 13, v[2:3]
	v_or_b32_e32 v2, 6, v30
	v_lshlrev_b64 v[58:59], 13, v[2:3]
	v_or_b32_e32 v2, 8, v30
	v_lshlrev_b64 v[60:61], 13, v[2:3]
	v_or_b32_e32 v2, 10, v30
	v_mov_b32_e32 v31, v3
	v_lshlrev_b64 v[62:63], 13, v[2:3]
	v_or_b32_e32 v2, 12, v30
	v_lshlrev_b64 v[52:53], 13, v[30:31]
	v_lshlrev_b64 v[64:65], 13, v[2:3]
	v_or_b32_e32 v2, 14, v30
	v_lshl_add_u64 v[52:53], v[50:51], 0, v[52:53]
	v_lshlrev_b64 v[66:67], 13, v[2:3]
	v_or_b32_e32 v2, 16, v30
	v_lshl_add_u64 v[54:55], v[50:51], 0, v[54:55]
	v_lshl_add_u64 v[56:57], v[50:51], 0, v[56:57]
	v_lshl_add_u64 v[58:59], v[50:51], 0, v[58:59]
	v_lshl_add_u64 v[60:61], v[50:51], 0, v[60:61]
	v_lshl_add_u64 v[62:63], v[50:51], 0, v[62:63]
	v_lshl_add_u64 v[64:65], v[50:51], 0, v[64:65]
	v_lshl_add_u64 v[66:67], v[50:51], 0, v[66:67]
	global_load_dword v29, v[52:53], off
	global_load_dword v68, v[54:55], off
	global_load_dword v69, v[56:57], off
	global_load_dword v70, v[58:59], off
	global_load_dword v71, v[60:61], off
	global_load_dword v72, v[62:63], off
	global_load_dword v73, v[64:65], off
	global_load_dword v74, v[66:67], off
	v_lshlrev_b64 v[52:53], 13, v[2:3]
	v_or_b32_e32 v2, 18, v30
	v_lshlrev_b64 v[54:55], 13, v[2:3]
	v_or_b32_e32 v2, 20, v30
	v_lshlrev_b64 v[56:57], 13, v[2:3]
	v_or_b32_e32 v2, 22, v30
	v_lshlrev_b64 v[58:59], 13, v[2:3]
	v_or_b32_e32 v2, 24, v30
	v_lshlrev_b64 v[60:61], 13, v[2:3]
	v_or_b32_e32 v2, 26, v30
	v_lshlrev_b64 v[62:63], 13, v[2:3]
	v_or_b32_e32 v2, 28, v30
	v_lshlrev_b64 v[64:65], 13, v[2:3]
	v_or_b32_e32 v2, 30, v30
	v_lshl_add_u64 v[52:53], v[50:51], 0, v[52:53]
	v_lshlrev_b64 v[66:67], 13, v[2:3]
	v_or_b32_e32 v2, 32, v30
	v_lshl_add_u64 v[54:55], v[50:51], 0, v[54:55]
	v_lshl_add_u64 v[56:57], v[50:51], 0, v[56:57]
	v_lshl_add_u64 v[58:59], v[50:51], 0, v[58:59]
	v_lshl_add_u64 v[60:61], v[50:51], 0, v[60:61]
	v_lshl_add_u64 v[62:63], v[50:51], 0, v[62:63]
	v_lshl_add_u64 v[64:65], v[50:51], 0, v[64:65]
	v_lshl_add_u64 v[66:67], v[50:51], 0, v[66:67]
	global_load_dword v75, v[52:53], off
	global_load_dword v76, v[54:55], off
	global_load_dword v77, v[56:57], off
	global_load_dword v78, v[58:59], off
	global_load_dword v79, v[60:61], off
	global_load_dword v80, v[62:63], off
	global_load_dword v81, v[64:65], off
	global_load_dword v82, v[66:67], off
	v_lshlrev_b64 v[52:53], 13, v[2:3]
	v_or_b32_e32 v2, 34, v30
	v_lshlrev_b64 v[54:55], 13, v[2:3]
	v_or_b32_e32 v2, 36, v30
	v_lshlrev_b64 v[56:57], 13, v[2:3]
	v_or_b32_e32 v2, 38, v30
	v_lshlrev_b64 v[58:59], 13, v[2:3]
	v_or_b32_e32 v2, 40, v30
	v_lshlrev_b64 v[60:61], 13, v[2:3]
	v_or_b32_e32 v2, 42, v30
	v_lshlrev_b64 v[62:63], 13, v[2:3]
	v_or_b32_e32 v2, 44, v30
	v_lshlrev_b64 v[64:65], 13, v[2:3]
	v_or_b32_e32 v2, 46, v30
	v_lshlrev_b64 v[66:67], 13, v[2:3]
	v_lshl_add_u64 v[52:53], v[50:51], 0, v[52:53]
	v_lshl_add_u64 v[66:67], v[50:51], 0, v[66:67]
	v_or_b32_e32 v2, 48, v30
	v_lshl_add_u64 v[54:55], v[50:51], 0, v[54:55]
	v_lshl_add_u64 v[56:57], v[50:51], 0, v[56:57]
	v_lshl_add_u64 v[58:59], v[50:51], 0, v[58:59]
	v_lshl_add_u64 v[60:61], v[50:51], 0, v[60:61]
	v_lshl_add_u64 v[62:63], v[50:51], 0, v[62:63]
	v_lshl_add_u64 v[64:65], v[50:51], 0, v[64:65]
	global_load_dword v83, v[52:53], off
	global_load_dword v84, v[54:55], off
	global_load_dword v85, v[56:57], off
	global_load_dword v86, v[58:59], off
	global_load_dword v87, v[60:61], off
	global_load_dword v88, v[62:63], off
	global_load_dword v89, v[64:65], off
	s_nop 0
	global_load_dword v66, v[66:67], off
	v_lshlrev_b64 v[52:53], 13, v[2:3]
	v_or_b32_e32 v2, 50, v30
	v_lshlrev_b64 v[54:55], 13, v[2:3]
	v_or_b32_e32 v2, 52, v30
	v_lshlrev_b64 v[56:57], 13, v[2:3]
	v_or_b32_e32 v2, 54, v30
	v_lshlrev_b64 v[58:59], 13, v[2:3]
	v_or_b32_e32 v2, 56, v30
	v_lshlrev_b64 v[60:61], 13, v[2:3]
	v_or_b32_e32 v2, 58, v30
	v_lshlrev_b64 v[62:63], 13, v[2:3]
	v_or_b32_e32 v2, 60, v30
	v_lshlrev_b64 v[64:65], 13, v[2:3]
	v_or_b32_e32 v2, 62, v30
	v_lshlrev_b64 v[30:31], 13, v[2:3]
	v_lshl_add_u64 v[52:53], v[50:51], 0, v[52:53]
	v_lshl_add_u64 v[54:55], v[50:51], 0, v[54:55]
	v_lshl_add_u64 v[30:31], v[50:51], 0, v[30:31]
	v_lshl_add_u64 v[56:57], v[50:51], 0, v[56:57]
	v_lshl_add_u64 v[58:59], v[50:51], 0, v[58:59]
	v_lshl_add_u64 v[60:61], v[50:51], 0, v[60:61]
	v_lshl_add_u64 v[62:63], v[50:51], 0, v[62:63]
	v_lshl_add_u64 v[64:65], v[50:51], 0, v[64:65]
	global_load_dword v2, v[52:53], off
	global_load_dword v50, v[54:55], off
	global_load_dword v51, v[56:57], off
	s_nop 0
	global_load_dword v52, v[58:59], off
	global_load_dword v53, v[60:61], off
	global_load_dword v54, v[62:63], off
	global_load_dword v55, v[64:65], off
	s_nop 0
	global_load_dword v30, v[30:31], off
	s_waitcnt vmcnt(30)
; __device__ __forceinline__ unsigned pk2(float lo, float hi) { unsigned r; asm("v_cvt_pk_bf16_f32 %0, %1, %2" : "=v"(r) : "v"(lo), "v"(hi)); return r; }
; __device__ __forceinline__ void transpose_item(const float* W, int ldw, int src0, int nvalid, int k0, int K, bf16_t* WT, int drow0, float* scr, int lane) {
;     ...
;     for (int i = 0; i < 32; ++i) { const int kk = 2 * i + (lane >> 5); tv[i] = (n_ < nvalid) ? W[(size_t)(k0 + kk) * ldw + src0 + n_] : 0.f; }
; #pragma unroll
;     for (int i = 0; i < 32; ++i) { const int kk = 2 * i + (lane >> 5); scr[kk * 33 + n_] = tv[i]; }
;     __builtin_amdgcn_s_waitcnt(0); asm volatile("" ::: "memory");
;     const int c = lane & 7;
; #pragma unroll
;     for (int j = 0; j < 4; ++j) { const int n = (lane >> 3) + 8 * j; const float* s = scr + (8 * c) * 33 + n;
;         u32x4 o; o.x = pk2(s[0 * 33], s[1 * 33]); o.y = pk2(s[2 * 33], s[3 * 33]); o.z = pk2(s[4 * 33], s[5 * 33]); o.w = pk2(s[6 * 33], s[7 * 33]);
;         *(u32x4*)(WT + (size_t)(drow0 + n) * K + k0 + 8 * c) = o; }
;     __builtin_amdgcn_s_waitcnt(0); asm volatile("" ::: "memory");
; __device__ __forceinline__ void phase_prologue(const Params& p, unsigned char* lds) {
;     ...
;         if (r < I_UP) { const int kb = r / 344, nb = r % 344, n0 = nb * 32, pt = n0 >> 8, l0 = n0 & 255;
;             const int src0 = (l0 < 128) ? pt * 128 + l0 : DFF + pt * 128 + (l0 - 128);
;             transpose_item(p.in[13], NUP, src0, 32, kb * 64, 2048, (bf16_t*)(ws + WS_WUP), n0, scr, lane); continue; }
	ds_write2_b32 v33, v29, v68 offset1:66
	s_waitcnt vmcnt(28)
	ds_write2_b32 v33, v69, v70 offset0:132 offset1:198
	s_waitcnt vmcnt(26)
	ds_write2_b32 v40, v71, v72 offset0:8 offset1:74
	s_waitcnt vmcnt(24)
	ds_write2_b32 v40, v73, v74 offset0:140 offset1:206
	s_waitcnt vmcnt(22)
	ds_write2_b32 v41, v75, v76 offset0:16 offset1:82
	s_waitcnt vmcnt(20)
	ds_write2_b32 v41, v77, v78 offset0:148 offset1:214
	s_waitcnt vmcnt(18)
	ds_write2_b32 v42, v79, v80 offset0:24 offset1:90
	s_waitcnt vmcnt(16)
	ds_write2_b32 v42, v81, v82 offset0:156 offset1:222
	s_waitcnt vmcnt(14)
	ds_write2_b32 v43, v83, v84 offset0:32 offset1:98
	s_waitcnt vmcnt(12)
	ds_write2_b32 v43, v85, v86 offset0:164 offset1:230
	s_waitcnt vmcnt(10)
	ds_write2_b32 v44, v87, v88 offset0:40 offset1:106
	s_waitcnt vmcnt(8)
	ds_write2_b32 v44, v89, v66 offset0:172 offset1:238
	s_waitcnt vmcnt(6)
	ds_write2_b32 v45, v2, v50 offset0:48 offset1:114
	s_waitcnt vmcnt(4)
	ds_write2_b32 v45, v51, v52 offset0:180 offset1:246
	s_waitcnt vmcnt(2)
	ds_write2_b32 v46, v53, v54 offset0:56 offset1:122
	s_waitcnt vmcnt(0)
	ds_write2_b32 v46, v55, v30 offset0:188 offset1:254
	s_waitcnt vmcnt(0) expcnt(0) lgkmcnt(0)
	v_or_b32_e32 v2, v49, v34
	v_mov_b32_e32 v29, v3
	ds_read2_b32 v[50:51], v35 offset0:33 offset1:41
	ds_read2_b32 v[52:53], v35 offset1:8
	ds_read2_b32 v[54:55], v35 offset0:66 offset1:74
	ds_read2_b32 v[56:57], v35 offset0:99 offset1:107
	ds_read2_b32 v[58:59], v35 offset0:132 offset1:140
	ds_read2_b32 v[60:61], v35 offset0:165 offset1:173
	ds_read2_b32 v[62:63], v35 offset0:198 offset1:206
	ds_read2_b32 v[64:65], v35 offset0:231 offset1:239
	v_mul_u32_u24_e32 v2, 0x1580, v2
	v_lshl_add_u64 v[66:67], v[28:29], 1, v[4:5]
	v_lshlrev_b32_e32 v2, 1, v2
	v_lshl_add_u64 v[68:69], v[66:67], 0, v[2:3]
	v_or_b32_e32 v2, v49, v36
	v_mul_u32_u24_e32 v2, 0x1580, v2
	s_waitcnt lgkmcnt(6)
	v_cvt_pk_bf16_f32 v28, v52, v50
	v_lshlrev_b32_e32 v2, 1, v2
	s_waitcnt lgkmcnt(4)
	v_cvt_pk_bf16_f32 v29, v54, v56
	s_waitcnt lgkmcnt(2)
	v_cvt_pk_bf16_f32 v30, v58, v60
	s_waitcnt lgkmcnt(0)
	v_cvt_pk_bf16_f32 v31, v62, v64
	global_store_dwordx4 v[68:69], v[28:31], off
	s_nop 1
	v_cvt_pk_bf16_f32 v28, v53, v51
	v_lshl_add_u64 v[50:51], v[66:67], 0, v[2:3]
	v_or_b32_e32 v2, v49, v37
	v_cvt_pk_bf16_f32 v29, v55, v57
	v_cvt_pk_bf16_f32 v30, v59, v61
	v_cvt_pk_bf16_f32 v31, v63, v65
	ds_read2_b32 v[52:53], v35 offset0:16 offset1:24
	ds_read2_b32 v[54:55], v35 offset0:49 offset1:57
	ds_read2_b32 v[56:57], v35 offset0:82 offset1:90
	ds_read2_b32 v[58:59], v35 offset0:115 offset1:123
	ds_read2_b32 v[60:61], v35 offset0:148 offset1:156
	ds_read2_b32 v[62:63], v35 offset0:181 offset1:189
	ds_read2_b32 v[64:65], v35 offset0:214 offset1:222
	ds_read2_b32 v[68:69], v35 offset0:247 offset1:255
	v_mul_u32_u24_e32 v2, 0x1580, v2
	v_lshlrev_b32_e32 v2, 1, v2
	global_store_dwordx4 v[50:51], v[28:31], off
	v_lshl_add_u64 v[50:51], v[66:67], 0, v[2:3]
	v_or_b32_e32 v2, v49, v38
	v_mul_u32_u24_e32 v2, 0x1580, v2
	v_lshlrev_b32_e32 v2, 1, v2
	s_waitcnt lgkmcnt(6)
	v_cvt_pk_bf16_f32 v28, v52, v54
	s_waitcnt lgkmcnt(4)
	v_cvt_pk_bf16_f32 v29, v56, v58
	s_waitcnt lgkmcnt(2)
	v_cvt_pk_bf16_f32 v30, v60, v62
	s_waitcnt lgkmcnt(0)
	v_cvt_pk_bf16_f32 v31, v64, v68
	global_store_dwordx4 v[50:51], v[28:31], off
	v_lshl_add_u64 v[50:51], v[66:67], 0, v[2:3]
	s_nop 0
	v_cvt_pk_bf16_f32 v28, v53, v55
	v_cvt_pk_bf16_f32 v29, v57, v59
	v_cvt_pk_bf16_f32 v30, v61, v63
	v_cvt_pk_bf16_f32 v31, v65, v69
	global_store_dwordx4 v[50:51], v[28:31], off
	s_waitcnt lgkmcnt(0)
.LBB0_16:
	s_andn2_saveexec_b64 s[18:19], s[0:1]
	s_cbranch_execz .LBB0_18
	v_add_u16_e32 v2, 0xc300, v1
	v_mul_u32_u24_e32 v28, 0xbe83, v2
	s_movk_i32 s0, 0x158
	v_mul_lo_u16_sdwa v29, v28, s0 dst_sel:DWORD dst_unused:UNUSED_PAD src0_sel:BYTE_3 src1_sel:DWORD
	v_sub_u16_e32 v2, v2, v29
	v_lshlrev_b32_e32 v49, 5, v2
	v_lshlrev_b32_e32 v2, 4, v2
	v_and_b32_e32 v29, 0xe0, v49
	v_and_b32_e32 v2, 0x1f80, v2
	s_movk_i32 s0, 0x1500
	v_or_b32_e32 v30, v2, v29
	v_add3_u32 v2, v2, v29, s0
	s_movk_i32 s0, 0x80
	v_cmp_gt_u32_e64 s[0:1], s0, v29
	v_lshlrev_b16_sdwa v64, v47, v28 dst_sel:DWORD dst_unused:UNUSED_PAD src0_sel:DWORD src1_sel:BYTE_3
	s_nop 0
	v_cndmask_b32_e64 v2, v2, v30, s[0:1]
	v_or_b32_e32 v30, v32, v64
	v_lshlrev_b32_e32 v2, 2, v2
	v_lshl_add_u64 v[28:29], v[18:19], 0, v[2:3]
	v_mul_u32_u24_e32 v2, 0x2b00, v30
	v_lshlrev_b32_e32 v2, 2, v2
	v_lshl_add_u64 v[28:29], v[28:29], 0, v[2:3]
	s_mov_b32 s0, 0x15000
	v_add_co_u32_e64 v30, s[0:1], s0, v28
	s_nop 1
	v_addc_co_u32_e64 v31, s[0:1], 0, v29, s[0:1]
	s_mov_b32 s0, 0x2b000
	s_nop 0
	v_add_co_u32_e64 v50, s[0:1], s0, v28
	s_nop 1
	v_addc_co_u32_e64 v51, s[0:1], 0, v29, s[0:1]
	s_mov_b32 s0, 0x40000
	s_nop 0
	v_add_co_u32_e64 v52, s[0:1], s0, v28
	s_nop 1
	v_addc_co_u32_e64 v53, s[0:1], 0, v29, s[0:1]
	v_add_co_u32_e64 v54, s[0:1], s38, v28
	s_nop 1
	v_addc_co_u32_e64 v55, s[0:1], 0, v29, s[0:1]
	v_add_co_u32_e64 v56, s[0:1], s39, v28
	s_nop 1
	v_addc_co_u32_e64 v57, s[0:1], 0, v29, s[0:1]
	v_add_co_u32_e64 v58, s[0:1], s40, v28
	s_nop 1
	v_addc_co_u32_e64 v59, s[0:1], 0, v29, s[0:1]
	v_add_co_u32_e64 v60, s[0:1], s41, v28
	s_nop 1
	v_addc_co_u32_e64 v61, s[0:1], 0, v29, s[0:1]
	global_load_dword v2, v[28:29], off
	global_load_dword v65, v[30:31], off offset:2048
	global_load_dword v66, v[50:51], off
	global_load_dword v67, v[52:53], off offset:2048
	global_load_dword v68, v[54:55], off
	global_load_dword v69, v[56:57], off offset:2048
	global_load_dword v70, v[58:59], off
	global_load_dword v71, v[60:61], off offset:2048
	v_add_co_u32_e64 v30, s[0:1], s42, v28
	s_nop 1
	v_addc_co_u32_e64 v31, s[0:1], 0, v29, s[0:1]
; __device__ __forceinline__ unsigned pk2(float lo, float hi) { unsigned r; asm("v_cvt_pk_bf16_f32 %0, %1, %2" : "=v"(r) : "v"(lo), "v"(hi)); return r; }
; __device__ __forceinline__ void transpose_item(const float* W, int ldw, int src0, int nvalid, int k0, int K, bf16_t* WT, int drow0, float* scr, int lane) {
;     ...
;     for (int i = 0; i < 32; ++i) { const int kk = 2 * i + (lane >> 5); tv[i] = (n_ < nvalid) ? W[(size_t)(k0 + kk) * ldw + src0 + n_] : 0.f; }
; #pragma unroll
;     for (int i = 0; i < 32; ++i) { const int kk = 2 * i + (lane >> 5); scr[kk * 33 + n_] = tv[i]; }
;     __builtin_amdgcn_s_waitcnt(0); asm volatile("" ::: "memory");
;     const int c = lane & 7;
; #pragma unroll
;     for (int j = 0; j < 4; ++j) { const int n = (lane >> 3) + 8 * j; const float* s = scr + (8 * c) * 33 + n;
;         u32x4 o; o.x = pk2(s[0 * 33], s[1 * 33]); o.y = pk2(s[2 * 33], s[3 * 33]); o.z = pk2(s[4 * 33], s[5 * 33]); o.w = pk2(s[6 * 33], s[7 * 33]);
;         *(u32x4*)(WT + (size_t)(drow0 + n) * K + k0 + 8 * c) = o; }
;     __builtin_amdgcn_s_waitcnt(0); asm volatile("" ::: "memory");
	v_add_co_u32_e64 v50, s[0:1], s43, v28
	s_nop 1
	v_addc_co_u32_e64 v51, s[0:1], 0, v29, s[0:1]
	v_add_co_u32_e64 v52, s[0:1], s44, v28
	s_nop 1
	v_addc_co_u32_e64 v53, s[0:1], 0, v29, s[0:1]
	v_add_co_u32_e64 v54, s[0:1], s45, v28
	s_nop 1
	v_addc_co_u32_e64 v55, s[0:1], 0, v29, s[0:1]
	v_add_co_u32_e64 v56, s[0:1], s46, v28
	s_nop 1
	v_addc_co_u32_e64 v57, s[0:1], 0, v29, s[0:1]
	v_add_co_u32_e64 v58, s[0:1], s47, v28
	s_nop 1
	v_addc_co_u32_e64 v59, s[0:1], 0, v29, s[0:1]
	v_add_co_u32_e64 v60, s[0:1], s48, v28
	s_nop 1
	v_addc_co_u32_e64 v61, s[0:1], 0, v29, s[0:1]
	v_add_co_u32_e64 v62, s[0:1], s49, v28
	s_nop 1
	v_addc_co_u32_e64 v63, s[0:1], 0, v29, s[0:1]
	global_load_dword v72, v[30:31], off
	global_load_dword v73, v[50:51], off offset:2048
	global_load_dword v74, v[52:53], off
	global_load_dword v75, v[54:55], off offset:2048
	global_load_dword v76, v[56:57], off
	global_load_dword v77, v[58:59], off offset:2048
	global_load_dword v78, v[60:61], off
	global_load_dword v79, v[62:63], off offset:2048
	v_add_co_u32_e64 v30, s[0:1], s50, v28
	s_nop 1
	v_addc_co_u32_e64 v31, s[0:1], 0, v29, s[0:1]
	v_add_co_u32_e64 v50, s[0:1], s51, v28
	s_nop 1
	v_addc_co_u32_e64 v51, s[0:1], 0, v29, s[0:1]
	v_add_co_u32_e64 v52, s[0:1], s52, v28
	s_nop 1
	v_addc_co_u32_e64 v53, s[0:1], 0, v29, s[0:1]
	v_add_co_u32_e64 v54, s[0:1], s53, v28
	s_nop 1
	v_addc_co_u32_e64 v55, s[0:1], 0, v29, s[0:1]
	v_add_co_u32_e64 v56, s[0:1], s54, v28
	s_nop 1
	v_addc_co_u32_e64 v57, s[0:1], 0, v29, s[0:1]
	v_add_co_u32_e64 v58, s[0:1], s55, v28
	s_nop 1
	v_addc_co_u32_e64 v59, s[0:1], 0, v29, s[0:1]
	v_add_co_u32_e64 v60, s[0:1], s56, v28
	s_nop 1
	v_addc_co_u32_e64 v61, s[0:1], 0, v29, s[0:1]
	v_add_co_u32_e64 v62, s[0:1], s57, v28
	s_nop 1
	v_addc_co_u32_e64 v63, s[0:1], 0, v29, s[0:1]
	global_load_dword v80, v[30:31], off
	global_load_dword v81, v[50:51], off offset:2048
	global_load_dword v82, v[52:53], off
	global_load_dword v83, v[54:55], off offset:2048
	global_load_dword v84, v[56:57], off
	global_load_dword v85, v[58:59], off offset:2048
	global_load_dword v86, v[60:61], off
	s_nop 0
	global_load_dword v62, v[62:63], off offset:2048
	v_add_co_u32_e64 v30, s[0:1], s58, v28
	s_nop 1
	v_addc_co_u32_e64 v31, s[0:1], 0, v29, s[0:1]
	v_add_co_u32_e64 v50, s[0:1], s59, v28
	s_nop 1
	v_addc_co_u32_e64 v51, s[0:1], 0, v29, s[0:1]
	v_add_co_u32_e64 v52, s[0:1], s60, v28
	s_nop 1
	v_addc_co_u32_e64 v53, s[0:1], 0, v29, s[0:1]
	v_add_co_u32_e64 v54, s[0:1], s61, v28
	s_nop 1
	v_addc_co_u32_e64 v55, s[0:1], 0, v29, s[0:1]
	v_add_co_u32_e64 v56, s[0:1], s62, v28
	s_nop 1
	v_addc_co_u32_e64 v57, s[0:1], 0, v29, s[0:1]
	v_add_co_u32_e64 v58, s[0:1], s63, v28
	s_nop 1
	v_addc_co_u32_e64 v59, s[0:1], 0, v29, s[0:1]
	v_add_co_u32_e64 v60, s[0:1], s64, v28
	s_nop 1
	v_addc_co_u32_e64 v61, s[0:1], 0, v29, s[0:1]
	v_add_co_u32_e64 v28, s[0:1], s65, v28
	s_nop 1
	v_addc_co_u32_e64 v29, s[0:1], 0, v29, s[0:1]
	global_load_dword v30, v[30:31], off
	s_nop 0
	global_load_dword v31, v[50:51], off offset:2048
	s_nop 0
	global_load_dword v50, v[52:53], off
	global_load_dword v51, v[54:55], off offset:2048
	s_nop 0
	global_load_dword v52, v[56:57], off
	global_load_dword v53, v[58:59], off offset:2048
	global_load_dword v54, v[60:61], off
	s_nop 0
	global_load_dword v28, v[28:29], off offset:2048
	s_waitcnt vmcnt(30)
	ds_write2_b32 v33, v2, v65 offset1:66
	s_waitcnt vmcnt(28)
	ds_write2_b32 v33, v66, v67 offset0:132 offset1:198
	s_waitcnt vmcnt(26)
	ds_write2_b32 v40, v68, v69 offset0:8 offset1:74
	s_waitcnt vmcnt(24)
	ds_write2_b32 v40, v70, v71 offset0:140 offset1:206
	s_waitcnt vmcnt(22)
	ds_write2_b32 v41, v72, v73 offset0:16 offset1:82
	s_waitcnt vmcnt(20)
	ds_write2_b32 v41, v74, v75 offset0:148 offset1:214
	s_waitcnt vmcnt(18)
	ds_write2_b32 v42, v76, v77 offset0:24 offset1:90
	s_waitcnt vmcnt(16)
	ds_write2_b32 v42, v78, v79 offset0:156 offset1:222
	s_waitcnt vmcnt(14)
	ds_write2_b32 v43, v80, v81 offset0:32 offset1:98
	s_waitcnt vmcnt(12)
	ds_write2_b32 v43, v82, v83 offset0:164 offset1:230
	s_waitcnt vmcnt(10)
	ds_write2_b32 v44, v84, v85 offset0:40 offset1:106
	s_waitcnt vmcnt(8)
	ds_write2_b32 v44, v86, v62 offset0:172 offset1:238
	s_waitcnt vmcnt(6)
	ds_write2_b32 v45, v30, v31 offset0:48 offset1:114
	s_waitcnt vmcnt(4)
	ds_write2_b32 v45, v50, v51 offset0:180 offset1:246
	s_waitcnt vmcnt(2)
	ds_write2_b32 v46, v52, v53 offset0:56 offset1:122
	s_waitcnt vmcnt(0)
	ds_write2_b32 v46, v54, v28 offset0:188 offset1:254
	s_waitcnt vmcnt(0) expcnt(0) lgkmcnt(0)
	v_lshlrev_b32_e32 v2, 1, v64
	ds_read2_b32 v[50:51], v35 offset0:33 offset1:41
	ds_read2_b32 v[52:53], v35 offset1:8
	ds_read2_b32 v[54:55], v35 offset0:66 offset1:74
	ds_read2_b32 v[56:57], v35 offset0:99 offset1:107
	ds_read2_b32 v[58:59], v35 offset0:132 offset1:140
	ds_read2_b32 v[60:61], v35 offset0:165 offset1:173
	ds_read2_b32 v[62:63], v35 offset0:198 offset1:206
	ds_read2_b32 v[64:65], v35 offset0:231 offset1:239
	v_lshl_add_u64 v[66:67], v[6:7], 0, v[2:3]
	v_or_b32_e32 v2, v49, v34
	v_lshlrev_b32_e32 v2, 12, v2
	v_lshl_add_u64 v[68:69], v[66:67], 0, v[2:3]
	s_waitcnt lgkmcnt(6)
	v_cvt_pk_bf16_f32 v28, v52, v50
	s_waitcnt lgkmcnt(4)
	v_cvt_pk_bf16_f32 v29, v54, v56
	s_waitcnt lgkmcnt(2)
	v_cvt_pk_bf16_f32 v30, v58, v60
	s_waitcnt lgkmcnt(0)
	v_cvt_pk_bf16_f32 v31, v62, v64
	global_store_dwordx4 v[68:69], v[28:31], off
	v_or_b32_e32 v2, v49, v36
	v_lshlrev_b32_e32 v2, 12, v2
	v_cvt_pk_bf16_f32 v28, v53, v51
	v_cvt_pk_bf16_f32 v29, v55, v57
	v_cvt_pk_bf16_f32 v30, v59, v61
	v_cvt_pk_bf16_f32 v31, v63, v65
	ds_read2_b32 v[52:53], v35 offset0:16 offset1:24
	ds_read2_b32 v[54:55], v35 offset0:49 offset1:57
	ds_read2_b32 v[56:57], v35 offset0:82 offset1:90
	ds_read2_b32 v[58:59], v35 offset0:115 offset1:123
	ds_read2_b32 v[60:61], v35 offset0:148 offset1:156
	ds_read2_b32 v[62:63], v35 offset0:181 offset1:189
	ds_read2_b32 v[64:65], v35 offset0:214 offset1:222
	ds_read2_b32 v[68:69], v35 offset0:247 offset1:255
	v_lshl_add_u64 v[50:51], v[66:67], 0, v[2:3]
	v_or_b32_e32 v2, v49, v37
	v_lshlrev_b32_e32 v2, 12, v2
	global_store_dwordx4 v[50:51], v[28:31], off
	v_lshl_add_u64 v[50:51], v[66:67], 0, v[2:3]
	v_or_b32_e32 v2, v49, v38
	v_lshlrev_b32_e32 v2, 12, v2
	s_waitcnt lgkmcnt(6)
	v_cvt_pk_bf16_f32 v28, v52, v54
	s_waitcnt lgkmcnt(4)
	v_cvt_pk_bf16_f32 v29, v56, v58
	s_waitcnt lgkmcnt(2)
	v_cvt_pk_bf16_f32 v30, v60, v62
	s_waitcnt lgkmcnt(0)
	v_cvt_pk_bf16_f32 v31, v64, v68
	global_store_dwordx4 v[50:51], v[28:31], off
	v_lshl_add_u64 v[50:51], v[66:67], 0, v[2:3]
	s_nop 0
	v_cvt_pk_bf16_f32 v28, v53, v55
	v_cvt_pk_bf16_f32 v29, v57, v59
	v_cvt_pk_bf16_f32 v30, v61, v63
	v_cvt_pk_bf16_f32 v31, v65, v69
	global_store_dwordx4 v[50:51], v[28:31], off
	s_waitcnt lgkmcnt(0)

; __device__ __forceinline__ void transpose_item(const float* W, int ldw, int src0, int nvalid, int k0, int K, bf16_t* WT, int drow0, float* scr, int lane) {
;     ...
;     for (int i = 0; i < 32; ++i) { const int kk = 2 * i + (lane >> 5); tv[i] = (n_ < nvalid) ? W[(size_t)(k0 + kk) * ldw + src0 + n_] : 0.f; }
; #pragma unroll
;     for (int i = 0; i < 32; ++i) { const int kk = 2 * i + (lane >> 5); scr[kk * 33 + n_] = tv[i]; }
; __device__ __forceinline__ void phase_prologue(const Params& p, unsigned char* lds) {
;     ...
;         if (r < I_OUT) { const int kb = r / 64, nb = r % 64; transpose_item(p.in[10], 2048, nb * 32, 32, kb * 64, 2048, (bf16_t*)(ws + WS_WOUT), nb * 32, scr, lane); continue; }
;         r -= I_OUT;
.LBB0_19:
	s_andn2_saveexec_b64 s[0:1], s[14:15]
	s_cbranch_execz .LBB0_21
	v_and_b32_e32 v2, 0x3fc0, v1
	v_add_u32_e32 v28, 0xffffcb00, v2
	v_and_b32_e32 v49, 0x7e0, v39
	v_or_b32_e32 v30, v28, v32
	v_lshlrev_b32_e32 v2, 2, v49
	v_lshl_add_u64 v[50:51], v[20:21], 0, v[2:3]
	v_or_b32_e32 v2, 2, v30
	v_lshlrev_b64 v[54:55], 13, v[2:3]
	v_or_b32_e32 v2, 4, v30
	v_lshlrev_b64 v[56:57], 13, v[2:3]
	v_or_b32_e32 v2, 6, v30
	v_lshlrev_b64 v[58:59], 13, v[2:3]
	v_or_b32_e32 v2, 8, v30
	v_lshlrev_b64 v[60:61], 13, v[2:3]
	v_or_b32_e32 v2, 10, v30
	v_mov_b32_e32 v31, v3
	v_lshlrev_b64 v[62:63], 13, v[2:3]
	v_or_b32_e32 v2, 12, v30
	v_lshlrev_b64 v[52:53], 13, v[30:31]
	v_lshlrev_b64 v[64:65], 13, v[2:3]
	v_or_b32_e32 v2, 14, v30
	v_lshl_add_u64 v[52:53], v[50:51], 0, v[52:53]
	v_lshlrev_b64 v[66:67], 13, v[2:3]
	v_or_b32_e32 v2, 16, v30
	v_lshl_add_u64 v[54:55], v[50:51], 0, v[54:55]
	v_lshl_add_u64 v[56:57], v[50:51], 0, v[56:57]
	v_lshl_add_u64 v[58:59], v[50:51], 0, v[58:59]
	v_lshl_add_u64 v[60:61], v[50:51], 0, v[60:61]
	v_lshl_add_u64 v[62:63], v[50:51], 0, v[62:63]
	v_lshl_add_u64 v[64:65], v[50:51], 0, v[64:65]
	v_lshl_add_u64 v[66:67], v[50:51], 0, v[66:67]
	global_load_dword v29, v[52:53], off
	global_load_dword v68, v[54:55], off
	global_load_dword v69, v[56:57], off
	global_load_dword v70, v[58:59], off
	global_load_dword v71, v[60:61], off
	global_load_dword v72, v[62:63], off
	global_load_dword v73, v[64:65], off
	global_load_dword v74, v[66:67], off
	v_lshlrev_b64 v[52:53], 13, v[2:3]
	v_or_b32_e32 v2, 18, v30
	v_lshlrev_b64 v[54:55], 13, v[2:3]
	v_or_b32_e32 v2, 20, v30
	v_lshlrev_b64 v[56:57], 13, v[2:3]
	v_or_b32_e32 v2, 22, v30
	v_lshlrev_b64 v[58:59], 13, v[2:3]
	v_or_b32_e32 v2, 24, v30
	v_lshlrev_b64 v[60:61], 13, v[2:3]
	v_or_b32_e32 v2, 26, v30
	v_lshlrev_b64 v[62:63], 13, v[2:3]
	v_or_b32_e32 v2, 28, v30
	v_lshlrev_b64 v[64:65], 13, v[2:3]
	v_or_b32_e32 v2, 30, v30
	v_lshl_add_u64 v[52:53], v[50:51], 0, v[52:53]
	v_lshlrev_b64 v[66:67], 13, v[2:3]
	v_or_b32_e32 v2, 32, v30
	v_lshl_add_u64 v[54:55], v[50:51], 0, v[54:55]
	v_lshl_add_u64 v[56:57], v[50:51], 0, v[56:57]
	v_lshl_add_u64 v[58:59], v[50:51], 0, v[58:59]
	v_lshl_add_u64 v[60:61], v[50:51], 0, v[60:61]
	v_lshl_add_u64 v[62:63], v[50:51], 0, v[62:63]
	v_lshl_add_u64 v[64:65], v[50:51], 0, v[64:65]
	v_lshl_add_u64 v[66:67], v[50:51], 0, v[66:67]
	global_load_dword v75, v[52:53], off
	global_load_dword v76, v[54:55], off
	global_load_dword v77, v[56:57], off
	global_load_dword v78, v[58:59], off
	global_load_dword v79, v[60:61], off
	global_load_dword v80, v[62:63], off
	global_load_dword v81, v[64:65], off
	global_load_dword v82, v[66:67], off
	v_lshlrev_b64 v[52:53], 13, v[2:3]
	v_or_b32_e32 v2, 34, v30
	v_lshlrev_b64 v[54:55], 13, v[2:3]
	v_or_b32_e32 v2, 36, v30
	v_lshlrev_b64 v[56:57], 13, v[2:3]
	v_or_b32_e32 v2, 38, v30
	v_lshlrev_b64 v[58:59], 13, v[2:3]
	v_or_b32_e32 v2, 40, v30
	v_lshlrev_b64 v[60:61], 13, v[2:3]
	v_or_b32_e32 v2, 42, v30
	v_lshlrev_b64 v[62:63], 13, v[2:3]
	v_or_b32_e32 v2, 44, v30
	v_lshlrev_b64 v[64:65], 13, v[2:3]
	v_or_b32_e32 v2, 46, v30
	v_lshlrev_b64 v[66:67], 13, v[2:3]
	v_lshl_add_u64 v[52:53], v[50:51], 0, v[52:53]
	v_lshl_add_u64 v[66:67], v[50:51], 0, v[66:67]
	v_or_b32_e32 v2, 48, v30
	v_lshl_add_u64 v[54:55], v[50:51], 0, v[54:55]
	v_lshl_add_u64 v[56:57], v[50:51], 0, v[56:57]
	v_lshl_add_u64 v[58:59], v[50:51], 0, v[58:59]
	v_lshl_add_u64 v[60:61], v[50:51], 0, v[60:61]
	v_lshl_add_u64 v[62:63], v[50:51], 0, v[62:63]
	v_lshl_add_u64 v[64:65], v[50:51], 0, v[64:65]
	global_load_dword v83, v[52:53], off
	global_load_dword v84, v[54:55], off
	global_load_dword v85, v[56:57], off
	global_load_dword v86, v[58:59], off
	global_load_dword v87, v[60:61], off
	global_load_dword v88, v[62:63], off
	global_load_dword v89, v[64:65], off
	s_nop 0
	global_load_dword v66, v[66:67], off
	v_lshlrev_b64 v[52:53], 13, v[2:3]
	v_or_b32_e32 v2, 50, v30
	v_lshlrev_b64 v[54:55], 13, v[2:3]
	v_or_b32_e32 v2, 52, v30
	v_lshlrev_b64 v[56:57], 13, v[2:3]
	v_or_b32_e32 v2, 54, v30
	v_lshlrev_b64 v[58:59], 13, v[2:3]
	v_or_b32_e32 v2, 56, v30
	v_lshlrev_b64 v[60:61], 13, v[2:3]
	v_or_b32_e32 v2, 58, v30
	v_lshlrev_b64 v[62:63], 13, v[2:3]
	v_or_b32_e32 v2, 60, v30
	v_lshlrev_b64 v[64:65], 13, v[2:3]
	v_or_b32_e32 v2, 62, v30
	v_lshlrev_b64 v[30:31], 13, v[2:3]
	v_lshl_add_u64 v[52:53], v[50:51], 0, v[52:53]
	v_lshl_add_u64 v[54:55], v[50:51], 0, v[54:55]
	v_lshl_add_u64 v[30:31], v[50:51], 0, v[30:31]
	v_lshl_add_u64 v[56:57], v[50:51], 0, v[56:57]
	v_lshl_add_u64 v[58:59], v[50:51], 0, v[58:59]
	v_lshl_add_u64 v[60:61], v[50:51], 0, v[60:61]
	v_lshl_add_u64 v[62:63], v[50:51], 0, v[62:63]
	v_lshl_add_u64 v[64:65], v[50:51], 0, v[64:65]
	global_load_dword v2, v[52:53], off
	global_load_dword v50, v[54:55], off
	global_load_dword v51, v[56:57], off
	s_nop 0
	global_load_dword v52, v[58:59], off
	global_load_dword v53, v[60:61], off
	global_load_dword v54, v[62:63], off
	global_load_dword v55, v[64:65], off
	s_nop 0
	global_load_dword v30, v[30:31], off
	s_waitcnt vmcnt(30)
; __device__ __forceinline__ unsigned pk2(float lo, float hi) { unsigned r; asm("v_cvt_pk_bf16_f32 %0, %1, %2" : "=v"(r) : "v"(lo), "v"(hi)); return r; }
; __device__ __forceinline__ void transpose_item(const float* W, int ldw, int src0, int nvalid, int k0, int K, bf16_t* WT, int drow0, float* scr, int lane) {
;     ...
; #pragma unroll
;     for (int i = 0; i < 32; ++i) { const int kk = 2 * i + (lane >> 5); scr[kk * 33 + n_] = tv[i]; }
;     __builtin_amdgcn_s_waitcnt(0); asm volatile("" ::: "memory");
;     const int c = lane & 7;
; #pragma unroll
;     for (int j = 0; j < 4; ++j) { const int n = (lane >> 3) + 8 * j; const float* s = scr + (8 * c) * 33 + n;
;         u32x4 o; o.x = pk2(s[0 * 33], s[1 * 33]); o.y = pk2(s[2 * 33], s[3 * 33]); o.z = pk2(s[4 * 33], s[5 * 33]); o.w = pk2(s[6 * 33], s[7 * 33]);
;         *(u32x4*)(WT + (size_t)(drow0 + n) * K + k0 + 8 * c) = o; }
;     __builtin_amdgcn_s_waitcnt(0); asm volatile("" ::: "memory");
	ds_write2_b32 v33, v29, v68 offset1:66
	s_waitcnt vmcnt(28)
	ds_write2_b32 v33, v69, v70 offset0:132 offset1:198
	s_waitcnt vmcnt(26)
	ds_write2_b32 v40, v71, v72 offset0:8 offset1:74
	s_waitcnt vmcnt(24)
	ds_write2_b32 v40, v73, v74 offset0:140 offset1:206
	s_waitcnt vmcnt(22)
	ds_write2_b32 v41, v75, v76 offset0:16 offset1:82
	s_waitcnt vmcnt(20)
	ds_write2_b32 v41, v77, v78 offset0:148 offset1:214
	s_waitcnt vmcnt(18)
	ds_write2_b32 v42, v79, v80 offset0:24 offset1:90
	s_waitcnt vmcnt(16)
	ds_write2_b32 v42, v81, v82 offset0:156 offset1:222
	s_waitcnt vmcnt(14)
	ds_write2_b32 v43, v83, v84 offset0:32 offset1:98
	s_waitcnt vmcnt(12)
	ds_write2_b32 v43, v85, v86 offset0:164 offset1:230
	s_waitcnt vmcnt(10)
	ds_write2_b32 v44, v87, v88 offset0:40 offset1:106
	s_waitcnt vmcnt(8)
	ds_write2_b32 v44, v89, v66 offset0:172 offset1:238
	s_waitcnt vmcnt(6)
	ds_write2_b32 v45, v2, v50 offset0:48 offset1:114
	s_waitcnt vmcnt(4)
	ds_write2_b32 v45, v51, v52 offset0:180 offset1:246
	s_waitcnt vmcnt(2)
	ds_write2_b32 v46, v53, v54 offset0:56 offset1:122
	s_waitcnt vmcnt(0)
	ds_write2_b32 v46, v55, v30 offset0:188 offset1:254
	s_waitcnt vmcnt(0) expcnt(0) lgkmcnt(0)
	ds_read2_b32 v[50:51], v35 offset0:33 offset1:41
	ds_read2_b32 v[52:53], v35 offset1:8
	ds_read2_b32 v[54:55], v35 offset0:66 offset1:74
	ds_read2_b32 v[56:57], v35 offset0:99 offset1:107
	ds_read2_b32 v[58:59], v35 offset0:132 offset1:140
	ds_read2_b32 v[60:61], v35 offset0:165 offset1:173
	ds_read2_b32 v[62:63], v35 offset0:198 offset1:206
	ds_read2_b32 v[64:65], v35 offset0:231 offset1:239
	v_mov_b32_e32 v29, v3
	v_or_b32_e32 v2, v49, v34
	v_lshl_add_u64 v[66:67], v[28:29], 1, v[8:9]
	v_lshlrev_b32_e32 v2, 12, v2
	v_lshl_add_u64 v[68:69], v[66:67], 0, v[2:3]
	s_waitcnt lgkmcnt(6)
	v_cvt_pk_bf16_f32 v28, v52, v50
	s_waitcnt lgkmcnt(4)
	v_cvt_pk_bf16_f32 v29, v54, v56
	s_waitcnt lgkmcnt(2)
	v_cvt_pk_bf16_f32 v30, v58, v60
	s_waitcnt lgkmcnt(0)
	v_cvt_pk_bf16_f32 v31, v62, v64
	global_store_dwordx4 v[68:69], v[28:31], off
	v_or_b32_e32 v2, v49, v36
	v_lshlrev_b32_e32 v2, 12, v2
	v_cvt_pk_bf16_f32 v28, v53, v51
	v_cvt_pk_bf16_f32 v29, v55, v57
	v_cvt_pk_bf16_f32 v30, v59, v61
	v_cvt_pk_bf16_f32 v31, v63, v65
	ds_read2_b32 v[52:53], v35 offset0:16 offset1:24
	ds_read2_b32 v[54:55], v35 offset0:49 offset1:57
	ds_read2_b32 v[56:57], v35 offset0:82 offset1:90
	ds_read2_b32 v[58:59], v35 offset0:115 offset1:123
	ds_read2_b32 v[60:61], v35 offset0:148 offset1:156
	ds_read2_b32 v[62:63], v35 offset0:181 offset1:189
	ds_read2_b32 v[64:65], v35 offset0:214 offset1:222
	ds_read2_b32 v[68:69], v35 offset0:247 offset1:255
	v_lshl_add_u64 v[50:51], v[66:67], 0, v[2:3]
	v_or_b32_e32 v2, v49, v37
	v_lshlrev_b32_e32 v2, 12, v2
	global_store_dwordx4 v[50:51], v[28:31], off
	v_lshl_add_u64 v[50:51], v[66:67], 0, v[2:3]
	v_or_b32_e32 v2, v49, v38
	v_lshlrev_b32_e32 v2, 12, v2
	s_waitcnt lgkmcnt(6)
	v_cvt_pk_bf16_f32 v28, v52, v54
	s_waitcnt lgkmcnt(4)
	v_cvt_pk_bf16_f32 v29, v56, v58
	s_waitcnt lgkmcnt(2)
	v_cvt_pk_bf16_f32 v30, v60, v62
	s_waitcnt lgkmcnt(0)
	v_cvt_pk_bf16_f32 v31, v64, v68
	global_store_dwordx4 v[50:51], v[28:31], off
	v_lshl_add_u64 v[50:51], v[66:67], 0, v[2:3]
	s_nop 0
	v_cvt_pk_bf16_f32 v28, v53, v55
	v_cvt_pk_bf16_f32 v29, v57, v59
	v_cvt_pk_bf16_f32 v30, v61, v63
	v_cvt_pk_bf16_f32 v31, v65, v69
	global_store_dwordx4 v[50:51], v[28:31], off
	s_waitcnt lgkmcnt(0)

; __device__ __forceinline__ void transpose_item(const float* W, int ldw, int src0, int nvalid, int k0, int K, bf16_t* WT, int drow0, float* scr, int lane) {
;     const int n_ = lane & 31;
;     float tv[32];
; #pragma unroll
;     for (int i = 0; i < 32; ++i) { const int kk = 2 * i + (lane >> 5); tv[i] = (n_ < nvalid) ? W[(size_t)(k0 + kk) * ldw + src0 + n_] : 0.f; }
; __device__ __forceinline__ void phase_prologue(const Params& p, unsigned char* lds) {
;     ...
;         if (r < I_BN) { const int kb = r / 64, nb = r % 64; transpose_item(p.in[9], 2048, nb * 32, 32, kb * 64, 1024, (bf16_t*)(ws + WS_WBML), nb * 32, scr, lane); continue; }
.LBB0_22:
	s_andn2_saveexec_b64 s[0:1], s[12:13]
	s_cbranch_execz .LBB0_24
	v_and_b32_e32 v2, 0x3fc0, v1
	v_add_u32_e32 v28, 0xffffcf00, v2
	v_and_b32_e32 v49, 0x7e0, v39
	v_or_b32_e32 v30, v28, v32
	v_lshlrev_b32_e32 v2, 2, v49
	v_lshl_add_u64 v[50:51], v[22:23], 0, v[2:3]
	v_or_b32_e32 v2, 2, v30
	v_lshlrev_b64 v[54:55], 13, v[2:3]
	v_or_b32_e32 v2, 4, v30
	v_lshlrev_b64 v[56:57], 13, v[2:3]
	v_or_b32_e32 v2, 6, v30
	v_lshlrev_b64 v[58:59], 13, v[2:3]
	v_or_b32_e32 v2, 8, v30
	v_lshlrev_b64 v[60:61], 13, v[2:3]
	v_or_b32_e32 v2, 10, v30
	v_mov_b32_e32 v31, v3
	v_lshlrev_b64 v[62:63], 13, v[2:3]
	v_or_b32_e32 v2, 12, v30
	v_lshlrev_b64 v[52:53], 13, v[30:31]
	v_lshlrev_b64 v[64:65], 13, v[2:3]
	v_or_b32_e32 v2, 14, v30
	v_lshl_add_u64 v[52:53], v[50:51], 0, v[52:53]
	v_lshlrev_b64 v[66:67], 13, v[2:3]
	v_or_b32_e32 v2, 16, v30
	v_lshl_add_u64 v[54:55], v[50:51], 0, v[54:55]
	v_lshl_add_u64 v[56:57], v[50:51], 0, v[56:57]
	v_lshl_add_u64 v[58:59], v[50:51], 0, v[58:59]
	v_lshl_add_u64 v[60:61], v[50:51], 0, v[60:61]
	v_lshl_add_u64 v[62:63], v[50:51], 0, v[62:63]
	v_lshl_add_u64 v[64:65], v[50:51], 0, v[64:65]
	v_lshl_add_u64 v[66:67], v[50:51], 0, v[66:67]
	global_load_dword v29, v[52:53], off
	global_load_dword v68, v[54:55], off
	global_load_dword v69, v[56:57], off
	global_load_dword v70, v[58:59], off
	global_load_dword v71, v[60:61], off
	global_load_dword v72, v[62:63], off
	global_load_dword v73, v[64:65], off
	global_load_dword v74, v[66:67], off
	v_lshlrev_b64 v[52:53], 13, v[2:3]
	v_or_b32_e32 v2, 18, v30
	v_lshlrev_b64 v[54:55], 13, v[2:3]
	v_or_b32_e32 v2, 20, v30
	v_lshlrev_b64 v[56:57], 13, v[2:3]
	v_or_b32_e32 v2, 22, v30
	v_lshlrev_b64 v[58:59], 13, v[2:3]
	v_or_b32_e32 v2, 24, v30
	v_lshlrev_b64 v[60:61], 13, v[2:3]
	v_or_b32_e32 v2, 26, v30
	v_lshlrev_b64 v[62:63], 13, v[2:3]
	v_or_b32_e32 v2, 28, v30
	v_lshlrev_b64 v[64:65], 13, v[2:3]
	v_or_b32_e32 v2, 30, v30
	v_lshl_add_u64 v[52:53], v[50:51], 0, v[52:53]
	v_lshlrev_b64 v[66:67], 13, v[2:3]
	v_or_b32_e32 v2, 32, v30
	v_lshl_add_u64 v[54:55], v[50:51], 0, v[54:55]
	v_lshl_add_u64 v[56:57], v[50:51], 0, v[56:57]
	v_lshl_add_u64 v[58:59], v[50:51], 0, v[58:59]
	v_lshl_add_u64 v[60:61], v[50:51], 0, v[60:61]
	v_lshl_add_u64 v[62:63], v[50:51], 0, v[62:63]
	v_lshl_add_u64 v[64:65], v[50:51], 0, v[64:65]
	v_lshl_add_u64 v[66:67], v[50:51], 0, v[66:67]
	global_load_dword v75, v[52:53], off
	global_load_dword v76, v[54:55], off
	global_load_dword v77, v[56:57], off
	global_load_dword v78, v[58:59], off
	global_load_dword v79, v[60:61], off
	global_load_dword v80, v[62:63], off
	global_load_dword v81, v[64:65], off
	global_load_dword v82, v[66:67], off
	v_lshlrev_b64 v[52:53], 13, v[2:3]
	v_or_b32_e32 v2, 34, v30
	v_lshlrev_b64 v[54:55], 13, v[2:3]
	v_or_b32_e32 v2, 36, v30
	v_lshlrev_b64 v[56:57], 13, v[2:3]
	v_or_b32_e32 v2, 38, v30
	v_lshlrev_b64 v[58:59], 13, v[2:3]
	v_or_b32_e32 v2, 40, v30
	v_lshlrev_b64 v[60:61], 13, v[2:3]
	v_or_b32_e32 v2, 42, v30
	v_lshlrev_b64 v[62:63], 13, v[2:3]
	v_or_b32_e32 v2, 44, v30
	v_lshlrev_b64 v[64:65], 13, v[2:3]
	v_or_b32_e32 v2, 46, v30
	v_lshlrev_b64 v[66:67], 13, v[2:3]
	v_lshl_add_u64 v[52:53], v[50:51], 0, v[52:53]
	v_lshl_add_u64 v[66:67], v[50:51], 0, v[66:67]
	v_or_b32_e32 v2, 48, v30
	v_lshl_add_u64 v[54:55], v[50:51], 0, v[54:55]
	v_lshl_add_u64 v[56:57], v[50:51], 0, v[56:57]
	v_lshl_add_u64 v[58:59], v[50:51], 0, v[58:59]
	v_lshl_add_u64 v[60:61], v[50:51], 0, v[60:61]
	v_lshl_add_u64 v[62:63], v[50:51], 0, v[62:63]
	v_lshl_add_u64 v[64:65], v[50:51], 0, v[64:65]
	global_load_dword v83, v[52:53], off
	global_load_dword v84, v[54:55], off
	global_load_dword v85, v[56:57], off
	global_load_dword v86, v[58:59], off
	global_load_dword v87, v[60:61], off
	global_load_dword v88, v[62:63], off
	global_load_dword v89, v[64:65], off
	s_nop 0
	global_load_dword v66, v[66:67], off
	v_lshlrev_b64 v[52:53], 13, v[2:3]
	v_or_b32_e32 v2, 50, v30
	v_lshlrev_b64 v[54:55], 13, v[2:3]
	v_or_b32_e32 v2, 52, v30
	v_lshlrev_b64 v[56:57], 13, v[2:3]
	v_or_b32_e32 v2, 54, v30
	v_lshlrev_b64 v[58:59], 13, v[2:3]
	v_or_b32_e32 v2, 56, v30
	v_lshlrev_b64 v[60:61], 13, v[2:3]
	v_or_b32_e32 v2, 58, v30
	v_lshlrev_b64 v[62:63], 13, v[2:3]
	v_or_b32_e32 v2, 60, v30
	v_lshlrev_b64 v[64:65], 13, v[2:3]
	v_or_b32_e32 v2, 62, v30
	v_lshlrev_b64 v[30:31], 13, v[2:3]
	v_lshl_add_u64 v[52:53], v[50:51], 0, v[52:53]
	v_lshl_add_u64 v[54:55], v[50:51], 0, v[54:55]
	v_lshl_add_u64 v[30:31], v[50:51], 0, v[30:31]
	v_lshl_add_u64 v[56:57], v[50:51], 0, v[56:57]
	v_lshl_add_u64 v[58:59], v[50:51], 0, v[58:59]
	v_lshl_add_u64 v[60:61], v[50:51], 0, v[60:61]
	v_lshl_add_u64 v[62:63], v[50:51], 0, v[62:63]
	v_lshl_add_u64 v[64:65], v[50:51], 0, v[64:65]
	global_load_dword v2, v[52:53], off
	global_load_dword v50, v[54:55], off
	global_load_dword v51, v[56:57], off
	s_nop 0
	global_load_dword v52, v[58:59], off
	global_load_dword v53, v[60:61], off
	global_load_dword v54, v[62:63], off
	global_load_dword v55, v[64:65], off
	s_nop 0
	global_load_dword v30, v[30:31], off
	s_waitcnt vmcnt(30)
; __device__ __forceinline__ unsigned pk2(float lo, float hi) { unsigned r; asm("v_cvt_pk_bf16_f32 %0, %1, %2" : "=v"(r) : "v"(lo), "v"(hi)); return r; }
; __device__ __forceinline__ void transpose_item(const float* W, int ldw, int src0, int nvalid, int k0, int K, bf16_t* WT, int drow0, float* scr, int lane) {
;     ...
; #pragma unroll
;     for (int i = 0; i < 32; ++i) { const int kk = 2 * i + (lane >> 5); scr[kk * 33 + n_] = tv[i]; }
;     __builtin_amdgcn_s_waitcnt(0); asm volatile("" ::: "memory");
;     const int c = lane & 7;
; #pragma unroll
;     for (int j = 0; j < 4; ++j) { const int n = (lane >> 3) + 8 * j; const float* s = scr + (8 * c) * 33 + n;
;         u32x4 o; o.x = pk2(s[0 * 33], s[1 * 33]); o.y = pk2(s[2 * 33], s[3 * 33]); o.z = pk2(s[4 * 33], s[5 * 33]); o.w = pk2(s[6 * 33], s[7 * 33]);
;         *(u32x4*)(WT + (size_t)(drow0 + n) * K + k0 + 8 * c) = o; }
;     __builtin_amdgcn_s_waitcnt(0); asm volatile("" ::: "memory");
	ds_write2_b32 v33, v29, v68 offset1:66
	s_waitcnt vmcnt(28)
	ds_write2_b32 v33, v69, v70 offset0:132 offset1:198
	s_waitcnt vmcnt(26)
	ds_write2_b32 v40, v71, v72 offset0:8 offset1:74
	s_waitcnt vmcnt(24)
	ds_write2_b32 v40, v73, v74 offset0:140 offset1:206
	s_waitcnt vmcnt(22)
	ds_write2_b32 v41, v75, v76 offset0:16 offset1:82
	s_waitcnt vmcnt(20)
	ds_write2_b32 v41, v77, v78 offset0:148 offset1:214
	s_waitcnt vmcnt(18)
	ds_write2_b32 v42, v79, v80 offset0:24 offset1:90
	s_waitcnt vmcnt(16)
	ds_write2_b32 v42, v81, v82 offset0:156 offset1:222
	s_waitcnt vmcnt(14)
	ds_write2_b32 v43, v83, v84 offset0:32 offset1:98
	s_waitcnt vmcnt(12)
	ds_write2_b32 v43, v85, v86 offset0:164 offset1:230
	s_waitcnt vmcnt(10)
	ds_write2_b32 v44, v87, v88 offset0:40 offset1:106
	s_waitcnt vmcnt(8)
	ds_write2_b32 v44, v89, v66 offset0:172 offset1:238
	s_waitcnt vmcnt(6)
	ds_write2_b32 v45, v2, v50 offset0:48 offset1:114
	s_waitcnt vmcnt(4)
	ds_write2_b32 v45, v51, v52 offset0:180 offset1:246
	s_waitcnt vmcnt(2)
	ds_write2_b32 v46, v53, v54 offset0:56 offset1:122
	s_waitcnt vmcnt(0)
	ds_write2_b32 v46, v55, v30 offset0:188 offset1:254
	s_waitcnt vmcnt(0) expcnt(0) lgkmcnt(0)
	ds_read2_b32 v[50:51], v35 offset0:33 offset1:41
	ds_read2_b32 v[52:53], v35 offset1:8
	ds_read2_b32 v[54:55], v35 offset0:66 offset1:74
	ds_read2_b32 v[56:57], v35 offset0:99 offset1:107
	ds_read2_b32 v[58:59], v35 offset0:132 offset1:140
	ds_read2_b32 v[60:61], v35 offset0:165 offset1:173
	ds_read2_b32 v[62:63], v35 offset0:198 offset1:206
	ds_read2_b32 v[64:65], v35 offset0:231 offset1:239
	v_mov_b32_e32 v29, v3
	v_or_b32_e32 v2, v49, v34
	v_lshl_add_u64 v[66:67], v[28:29], 1, v[10:11]
	v_lshlrev_b32_e32 v2, 11, v2
	v_lshl_add_u64 v[68:69], v[66:67], 0, v[2:3]
	s_waitcnt lgkmcnt(6)
	v_cvt_pk_bf16_f32 v28, v52, v50
	s_waitcnt lgkmcnt(4)
	v_cvt_pk_bf16_f32 v29, v54, v56
	s_waitcnt lgkmcnt(2)
	v_cvt_pk_bf16_f32 v30, v58, v60
	s_waitcnt lgkmcnt(0)
	v_cvt_pk_bf16_f32 v31, v62, v64
	global_store_dwordx4 v[68:69], v[28:31], off
	v_or_b32_e32 v2, v49, v36
	v_lshlrev_b32_e32 v2, 11, v2
	v_cvt_pk_bf16_f32 v28, v53, v51
	v_cvt_pk_bf16_f32 v29, v55, v57
	v_cvt_pk_bf16_f32 v30, v59, v61
	v_cvt_pk_bf16_f32 v31, v63, v65
	ds_read2_b32 v[52:53], v35 offset0:16 offset1:24
	ds_read2_b32 v[54:55], v35 offset0:49 offset1:57
	ds_read2_b32 v[56:57], v35 offset0:82 offset1:90
	ds_read2_b32 v[58:59], v35 offset0:115 offset1:123
	ds_read2_b32 v[60:61], v35 offset0:148 offset1:156
	ds_read2_b32 v[62:63], v35 offset0:181 offset1:189
	ds_read2_b32 v[64:65], v35 offset0:214 offset1:222
	ds_read2_b32 v[68:69], v35 offset0:247 offset1:255
	v_lshl_add_u64 v[50:51], v[66:67], 0, v[2:3]
	v_or_b32_e32 v2, v49, v37
	v_lshlrev_b32_e32 v2, 11, v2
	global_store_dwordx4 v[50:51], v[28:31], off
	v_lshl_add_u64 v[50:51], v[66:67], 0, v[2:3]
	v_or_b32_e32 v2, v49, v38
	v_lshlrev_b32_e32 v2, 11, v2
	s_waitcnt lgkmcnt(6)
	v_cvt_pk_bf16_f32 v28, v52, v54
	s_waitcnt lgkmcnt(4)
	v_cvt_pk_bf16_f32 v29, v56, v58
	s_waitcnt lgkmcnt(2)
	v_cvt_pk_bf16_f32 v30, v60, v62
	s_waitcnt lgkmcnt(0)
	v_cvt_pk_bf16_f32 v31, v64, v68
	global_store_dwordx4 v[50:51], v[28:31], off
	v_lshl_add_u64 v[50:51], v[66:67], 0, v[2:3]
	s_nop 0
	v_cvt_pk_bf16_f32 v28, v53, v55
	v_cvt_pk_bf16_f32 v29, v57, v59
	v_cvt_pk_bf16_f32 v30, v61, v63
	v_cvt_pk_bf16_f32 v31, v65, v69
	global_store_dwordx4 v[50:51], v[28:31], off
	s_waitcnt lgkmcnt(0)

; __device__ __forceinline__ void transpose_item(const float* W, int ldw, int src0, int nvalid, int k0, int K, bf16_t* WT, int drow0, float* scr, int lane) {
;     const int n_ = lane & 31;
;     float tv[32];
; #pragma unroll
;     for (int i = 0; i < 32; ++i) { const int kk = 2 * i + (lane >> 5); tv[i] = (n_ < nvalid) ? W[(size_t)(k0 + kk) * ldw + src0 + n_] : 0.f; }
; __device__ __forceinline__ void phase_prologue(const Params& p, unsigned char* lds) {
;     ...
;         if (r < I_BN) { const int kb = r / 64, nb = r % 64; transpose_item(p.in[8], 2048, nb * 32, 32, kb * 64, 1024, (bf16_t*)(ws + WS_WBNA), nb * 32, scr, lane); continue; }
.LBB0_25:
	s_andn2_saveexec_b64 s[0:1], s[10:11]
	s_cbranch_execz .LBB0_27
	v_and_b32_e32 v2, 0x3fc0, v1
	v_add_u32_e32 v28, 0xffffd300, v2
	v_and_b32_e32 v49, 0x7e0, v39
	v_or_b32_e32 v30, v28, v32
	v_lshlrev_b32_e32 v2, 2, v49
	v_lshl_add_u64 v[50:51], v[24:25], 0, v[2:3]
	v_or_b32_e32 v2, 2, v30
	v_lshlrev_b64 v[54:55], 13, v[2:3]
	v_or_b32_e32 v2, 4, v30
	v_lshlrev_b64 v[56:57], 13, v[2:3]
	v_or_b32_e32 v2, 6, v30
	v_lshlrev_b64 v[58:59], 13, v[2:3]
	v_or_b32_e32 v2, 8, v30
	v_lshlrev_b64 v[60:61], 13, v[2:3]
	v_or_b32_e32 v2, 10, v30
	v_mov_b32_e32 v31, v3
	v_lshlrev_b64 v[62:63], 13, v[2:3]
	v_or_b32_e32 v2, 12, v30
	v_lshlrev_b64 v[52:53], 13, v[30:31]
	v_lshlrev_b64 v[64:65], 13, v[2:3]
	v_or_b32_e32 v2, 14, v30
	v_lshl_add_u64 v[52:53], v[50:51], 0, v[52:53]
	v_lshlrev_b64 v[66:67], 13, v[2:3]
	v_or_b32_e32 v2, 16, v30
	v_lshl_add_u64 v[54:55], v[50:51], 0, v[54:55]
	v_lshl_add_u64 v[56:57], v[50:51], 0, v[56:57]
	v_lshl_add_u64 v[58:59], v[50:51], 0, v[58:59]
	v_lshl_add_u64 v[60:61], v[50:51], 0, v[60:61]
	v_lshl_add_u64 v[62:63], v[50:51], 0, v[62:63]
	v_lshl_add_u64 v[64:65], v[50:51], 0, v[64:65]
	v_lshl_add_u64 v[66:67], v[50:51], 0, v[66:67]
	global_load_dword v29, v[52:53], off
	global_load_dword v68, v[54:55], off
	global_load_dword v69, v[56:57], off
	global_load_dword v70, v[58:59], off
	global_load_dword v71, v[60:61], off
	global_load_dword v72, v[62:63], off
	global_load_dword v73, v[64:65], off
	global_load_dword v74, v[66:67], off
	v_lshlrev_b64 v[52:53], 13, v[2:3]
	v_or_b32_e32 v2, 18, v30
	v_lshlrev_b64 v[54:55], 13, v[2:3]
	v_or_b32_e32 v2, 20, v30
	v_lshlrev_b64 v[56:57], 13, v[2:3]
	v_or_b32_e32 v2, 22, v30
	v_lshlrev_b64 v[58:59], 13, v[2:3]
	v_or_b32_e32 v2, 24, v30
	v_lshlrev_b64 v[60:61], 13, v[2:3]
	v_or_b32_e32 v2, 26, v30
	v_lshlrev_b64 v[62:63], 13, v[2:3]
	v_or_b32_e32 v2, 28, v30
	v_lshlrev_b64 v[64:65], 13, v[2:3]
	v_or_b32_e32 v2, 30, v30
	v_lshl_add_u64 v[52:53], v[50:51], 0, v[52:53]
	v_lshlrev_b64 v[66:67], 13, v[2:3]
	v_or_b32_e32 v2, 32, v30
	v_lshl_add_u64 v[54:55], v[50:51], 0, v[54:55]
	v_lshl_add_u64 v[56:57], v[50:51], 0, v[56:57]
	v_lshl_add_u64 v[58:59], v[50:51], 0, v[58:59]
	v_lshl_add_u64 v[60:61], v[50:51], 0, v[60:61]
	v_lshl_add_u64 v[62:63], v[50:51], 0, v[62:63]
	v_lshl_add_u64 v[64:65], v[50:51], 0, v[64:65]
	v_lshl_add_u64 v[66:67], v[50:51], 0, v[66:67]
	global_load_dword v75, v[52:53], off
	global_load_dword v76, v[54:55], off
	global_load_dword v77, v[56:57], off
	global_load_dword v78, v[58:59], off
	global_load_dword v79, v[60:61], off
	global_load_dword v80, v[62:63], off
	global_load_dword v81, v[64:65], off
	global_load_dword v82, v[66:67], off
	v_lshlrev_b64 v[52:53], 13, v[2:3]
	v_or_b32_e32 v2, 34, v30
	v_lshlrev_b64 v[54:55], 13, v[2:3]
	v_or_b32_e32 v2, 36, v30
	v_lshlrev_b64 v[56:57], 13, v[2:3]
	v_or_b32_e32 v2, 38, v30
	v_lshlrev_b64 v[58:59], 13, v[2:3]
	v_or_b32_e32 v2, 40, v30
	v_lshlrev_b64 v[60:61], 13, v[2:3]
	v_or_b32_e32 v2, 42, v30
	v_lshlrev_b64 v[62:63], 13, v[2:3]
	v_or_b32_e32 v2, 44, v30
	v_lshlrev_b64 v[64:65], 13, v[2:3]
	v_or_b32_e32 v2, 46, v30
	v_lshlrev_b64 v[66:67], 13, v[2:3]
	v_lshl_add_u64 v[52:53], v[50:51], 0, v[52:53]
	v_lshl_add_u64 v[66:67], v[50:51], 0, v[66:67]
	v_or_b32_e32 v2, 48, v30
	v_lshl_add_u64 v[54:55], v[50:51], 0, v[54:55]
	v_lshl_add_u64 v[56:57], v[50:51], 0, v[56:57]
	v_lshl_add_u64 v[58:59], v[50:51], 0, v[58:59]
	v_lshl_add_u64 v[60:61], v[50:51], 0, v[60:61]
	v_lshl_add_u64 v[62:63], v[50:51], 0, v[62:63]
	v_lshl_add_u64 v[64:65], v[50:51], 0, v[64:65]
	global_load_dword v83, v[52:53], off
	global_load_dword v84, v[54:55], off
	global_load_dword v85, v[56:57], off
	global_load_dword v86, v[58:59], off
	global_load_dword v87, v[60:61], off
	global_load_dword v88, v[62:63], off
	global_load_dword v89, v[64:65], off
	s_nop 0
	global_load_dword v66, v[66:67], off
	v_lshlrev_b64 v[52:53], 13, v[2:3]
	v_or_b32_e32 v2, 50, v30
	v_lshlrev_b64 v[54:55], 13, v[2:3]
	v_or_b32_e32 v2, 52, v30
	v_lshlrev_b64 v[56:57], 13, v[2:3]
	v_or_b32_e32 v2, 54, v30
	v_lshlrev_b64 v[58:59], 13, v[2:3]
	v_or_b32_e32 v2, 56, v30
	v_lshlrev_b64 v[60:61], 13, v[2:3]
	v_or_b32_e32 v2, 58, v30
	v_lshlrev_b64 v[62:63], 13, v[2:3]
	v_or_b32_e32 v2, 60, v30
	v_lshlrev_b64 v[64:65], 13, v[2:3]
	v_or_b32_e32 v2, 62, v30
	v_lshlrev_b64 v[30:31], 13, v[2:3]
	v_lshl_add_u64 v[52:53], v[50:51], 0, v[52:53]
	v_lshl_add_u64 v[54:55], v[50:51], 0, v[54:55]
	v_lshl_add_u64 v[30:31], v[50:51], 0, v[30:31]
	v_lshl_add_u64 v[56:57], v[50:51], 0, v[56:57]
	v_lshl_add_u64 v[58:59], v[50:51], 0, v[58:59]
	v_lshl_add_u64 v[60:61], v[50:51], 0, v[60:61]
	v_lshl_add_u64 v[62:63], v[50:51], 0, v[62:63]
	v_lshl_add_u64 v[64:65], v[50:51], 0, v[64:65]
	global_load_dword v2, v[52:53], off
	global_load_dword v50, v[54:55], off
	global_load_dword v51, v[56:57], off
	s_nop 0
	global_load_dword v52, v[58:59], off
	global_load_dword v53, v[60:61], off
	global_load_dword v54, v[62:63], off
	global_load_dword v55, v[64:65], off
	s_nop 0
	global_load_dword v30, v[30:31], off
	s_waitcnt vmcnt(30)
; __device__ __forceinline__ unsigned pk2(float lo, float hi) { unsigned r; asm("v_cvt_pk_bf16_f32 %0, %1, %2" : "=v"(r) : "v"(lo), "v"(hi)); return r; }
; __device__ __forceinline__ void transpose_item(const float* W, int ldw, int src0, int nvalid, int k0, int K, bf16_t* WT, int drow0, float* scr, int lane) {
;     ...
; #pragma unroll
;     for (int i = 0; i < 32; ++i) { const int kk = 2 * i + (lane >> 5); scr[kk * 33 + n_] = tv[i]; }
;     __builtin_amdgcn_s_waitcnt(0); asm volatile("" ::: "memory");
;     const int c = lane & 7;
; #pragma unroll
;     for (int j = 0; j < 4; ++j) { const int n = (lane >> 3) + 8 * j; const float* s = scr + (8 * c) * 33 + n;
;         u32x4 o; o.x = pk2(s[0 * 33], s[1 * 33]); o.y = pk2(s[2 * 33], s[3 * 33]); o.z = pk2(s[4 * 33], s[5 * 33]); o.w = pk2(s[6 * 33], s[7 * 33]);
;         *(u32x4*)(WT + (size_t)(drow0 + n) * K + k0 + 8 * c) = o; }
;     __builtin_amdgcn_s_waitcnt(0); asm volatile("" ::: "memory");
	ds_write2_b32 v33, v29, v68 offset1:66
	s_waitcnt vmcnt(28)
	ds_write2_b32 v33, v69, v70 offset0:132 offset1:198
	s_waitcnt vmcnt(26)
	ds_write2_b32 v40, v71, v72 offset0:8 offset1:74
	s_waitcnt vmcnt(24)
	ds_write2_b32 v40, v73, v74 offset0:140 offset1:206
	s_waitcnt vmcnt(22)
	ds_write2_b32 v41, v75, v76 offset0:16 offset1:82
	s_waitcnt vmcnt(20)
	ds_write2_b32 v41, v77, v78 offset0:148 offset1:214
	s_waitcnt vmcnt(18)
	ds_write2_b32 v42, v79, v80 offset0:24 offset1:90
	s_waitcnt vmcnt(16)
	ds_write2_b32 v42, v81, v82 offset0:156 offset1:222
	s_waitcnt vmcnt(14)
	ds_write2_b32 v43, v83, v84 offset0:32 offset1:98
	s_waitcnt vmcnt(12)
	ds_write2_b32 v43, v85, v86 offset0:164 offset1:230
	s_waitcnt vmcnt(10)
	ds_write2_b32 v44, v87, v88 offset0:40 offset1:106
	s_waitcnt vmcnt(8)
	ds_write2_b32 v44, v89, v66 offset0:172 offset1:238
	s_waitcnt vmcnt(6)
	ds_write2_b32 v45, v2, v50 offset0:48 offset1:114
	s_waitcnt vmcnt(4)
	ds_write2_b32 v45, v51, v52 offset0:180 offset1:246
	s_waitcnt vmcnt(2)
	ds_write2_b32 v46, v53, v54 offset0:56 offset1:122
	s_waitcnt vmcnt(0)
	ds_write2_b32 v46, v55, v30 offset0:188 offset1:254
	s_waitcnt vmcnt(0) expcnt(0) lgkmcnt(0)
	ds_read2_b32 v[50:51], v35 offset0:33 offset1:41
	ds_read2_b32 v[52:53], v35 offset1:8
	ds_read2_b32 v[54:55], v35 offset0:66 offset1:74
	ds_read2_b32 v[56:57], v35 offset0:99 offset1:107
	ds_read2_b32 v[58:59], v35 offset0:132 offset1:140
	ds_read2_b32 v[60:61], v35 offset0:165 offset1:173
	ds_read2_b32 v[62:63], v35 offset0:198 offset1:206
	ds_read2_b32 v[64:65], v35 offset0:231 offset1:239
	v_mov_b32_e32 v29, v3
	v_or_b32_e32 v2, v49, v34
	v_lshl_add_u64 v[66:67], v[28:29], 1, v[12:13]
	v_lshlrev_b32_e32 v2, 11, v2
	v_lshl_add_u64 v[68:69], v[66:67], 0, v[2:3]
	s_waitcnt lgkmcnt(6)
	v_cvt_pk_bf16_f32 v28, v52, v50
	s_waitcnt lgkmcnt(4)
	v_cvt_pk_bf16_f32 v29, v54, v56
	s_waitcnt lgkmcnt(2)
	v_cvt_pk_bf16_f32 v30, v58, v60
	s_waitcnt lgkmcnt(0)
	v_cvt_pk_bf16_f32 v31, v62, v64
	global_store_dwordx4 v[68:69], v[28:31], off
	v_or_b32_e32 v2, v49, v36
	v_lshlrev_b32_e32 v2, 11, v2
	v_cvt_pk_bf16_f32 v28, v53, v51
	v_cvt_pk_bf16_f32 v29, v55, v57
	v_cvt_pk_bf16_f32 v30, v59, v61
	v_cvt_pk_bf16_f32 v31, v63, v65
	ds_read2_b32 v[52:53], v35 offset0:16 offset1:24
	ds_read2_b32 v[54:55], v35 offset0:49 offset1:57
	ds_read2_b32 v[56:57], v35 offset0:82 offset1:90
	ds_read2_b32 v[58:59], v35 offset0:115 offset1:123
	ds_read2_b32 v[60:61], v35 offset0:148 offset1:156
	ds_read2_b32 v[62:63], v35 offset0:181 offset1:189
	ds_read2_b32 v[64:65], v35 offset0:214 offset1:222
	ds_read2_b32 v[68:69], v35 offset0:247 offset1:255
	v_lshl_add_u64 v[50:51], v[66:67], 0, v[2:3]
	v_or_b32_e32 v2, v49, v37
	v_lshlrev_b32_e32 v2, 11, v2
	global_store_dwordx4 v[50:51], v[28:31], off
	v_lshl_add_u64 v[50:51], v[66:67], 0, v[2:3]
	v_or_b32_e32 v2, v49, v38
	v_lshlrev_b32_e32 v2, 11, v2
	s_waitcnt lgkmcnt(6)
	v_cvt_pk_bf16_f32 v28, v52, v54
	s_waitcnt lgkmcnt(4)
	v_cvt_pk_bf16_f32 v29, v56, v58
	s_waitcnt lgkmcnt(2)
	v_cvt_pk_bf16_f32 v30, v60, v62
	s_waitcnt lgkmcnt(0)
	v_cvt_pk_bf16_f32 v31, v64, v68
	global_store_dwordx4 v[50:51], v[28:31], off
	v_lshl_add_u64 v[50:51], v[66:67], 0, v[2:3]
	s_nop 0
	v_cvt_pk_bf16_f32 v28, v53, v55
	v_cvt_pk_bf16_f32 v29, v57, v59
	v_cvt_pk_bf16_f32 v30, v61, v63
	v_cvt_pk_bf16_f32 v31, v65, v69
	global_store_dwordx4 v[50:51], v[28:31], off
	s_waitcnt lgkmcnt(0)
